# attention work queues: after a failed pop, peek all 8 queue heads in one round trip and skip exhausted queues
# baseline (speedup 1.0000x reference)
.Lattn_q_retry:
	s_cmp_gt_u32 s100, 7
	s_cbranch_scc1 .Lattn_q_none
	s_add_i32 s0, s101, s100
	s_and_b32 s0, s0, 7
	s_lshl_b32 s68, s0, 6
	v_mov_b32_e32 v0, s68
	v_mov_b32_e32 v1, 1
	global_atomic_add v1, v0, v1, s[42:43] sc0
	s_waitcnt vmcnt(0)
	v_readfirstlane_b32 s69, v1
	s_nop 3
	s_cmp_lt_u32 s69, 0x100
	s_cbranch_scc1 .Lattn_q_got
	s_add_i32 s100, s100, 1
	s_cmp_gt_u32 s100, 7
	s_cbranch_scc1 .Lattn_q_none
	v_mov_b32_e32 v0, 0
	global_load_dword v214, v0, s[42:43] sc1
	global_load_dword v215, v0, s[42:43] offset:64 sc1
	global_load_dword v216, v0, s[42:43] offset:128 sc1
	global_load_dword v217, v0, s[42:43] offset:192 sc1
	global_load_dword v218, v0, s[42:43] offset:256 sc1
	global_load_dword v219, v0, s[42:43] offset:320 sc1
	global_load_dword v220, v0, s[42:43] offset:384 sc1
	global_load_dword v221, v0, s[42:43] offset:448 sc1
	s_waitcnt vmcnt(0)
	s_mov_b32 s68, 0
	v_readfirstlane_b32 s69, v214
	s_nop 0
	s_cmp_lt_u32 s69, 0x100
	s_cselect_b32 s69, 0x1, 0
	s_or_b32 s68, s68, s69
	v_readfirstlane_b32 s69, v215
	s_nop 0
	s_cmp_lt_u32 s69, 0x100
	s_cselect_b32 s69, 0x2, 0
	s_or_b32 s68, s68, s69
	v_readfirstlane_b32 s69, v216
	s_nop 0
	s_cmp_lt_u32 s69, 0x100
	s_cselect_b32 s69, 0x4, 0
	s_or_b32 s68, s68, s69
	v_readfirstlane_b32 s69, v217
	s_nop 0
	s_cmp_lt_u32 s69, 0x100
	s_cselect_b32 s69, 0x8, 0
	s_or_b32 s68, s68, s69
	v_readfirstlane_b32 s69, v218
	s_nop 0
	s_cmp_lt_u32 s69, 0x100
	s_cselect_b32 s69, 0x10, 0
	s_or_b32 s68, s68, s69
	v_readfirstlane_b32 s69, v219
	s_nop 0
	s_cmp_lt_u32 s69, 0x100
	s_cselect_b32 s69, 0x20, 0
	s_or_b32 s68, s68, s69
	v_readfirstlane_b32 s69, v220
	s_nop 0
	s_cmp_lt_u32 s69, 0x100
	s_cselect_b32 s69, 0x40, 0
	s_or_b32 s68, s68, s69
	v_readfirstlane_b32 s69, v221
	s_nop 0
	s_cmp_lt_u32 s69, 0x100
	s_cselect_b32 s69, 0x80, 0
	s_or_b32 s68, s68, s69
.Lattn_q_skip:
	s_cmp_gt_u32 s100, 7
	s_cbranch_scc1 .Lattn_q_none
	s_add_i32 s0, s101, s100
	s_and_b32 s0, s0, 7
	s_lshr_b32 s69, s68, s0
	s_and_b32 s69, s69, 1
	s_cmp_lg_u32 s69, 0
	s_cbranch_scc1 .Lattn_q_retry
	s_add_i32 s100, s100, 1
	s_branch .Lattn_q_skip
